# dense attention as a ping-pong: wave halves alternate an MFMA segment (PV+QK) and a VALU segment (softmax), 2 barriers per tile
# baseline (speedup 1.0000x reference)
.LBB0_1012:
	s_ashr_i32 s39, s0, 7
	s_lshl_b32 s4, s0, 9
	s_bfe_u32 s1, s0, 0x40003
	s_and_b32 s40, s4, 0xe00
	s_lshl_b32 s4, s39, 4
	s_or_b32 s4, s4, s1
	s_add_i32 s40, s40, s38
	s_ashr_i32 s5, s4, 31
	s_lshr_b32 s6, s0, 3
	s_lshl_b64 s[4:5], s[4:5], 12
	s_ashr_i32 s7, s40, 31
	s_add_u32 s4, s4, s40
	s_addc_u32 s5, s5, s7
	v_mov_b32_e32 v1, s5
	v_or_b32_e32 v0, s4, v202
	s_bfe_u32 s4, s6, 0x20002
	s_lshl_b32 s5, s39, 2
	s_or_b32 s4, s4, s5
	v_lshlrev_b64 v[0:1], 7, v[0:1]
	s_ashr_i32 s5, s4, 31
	v_lshl_add_u64 v[2:3], v[204:205], 0, v[0:1]
	v_or_b32_e32 v0, 0x1000, v0
	s_lshl_b64 s[4:5], s[4:5], 19
	v_lshl_add_u64 v[0:1], v[204:205], 0, v[0:1]
	v_lshl_add_u64 v[212:213], v[208:209], 0, s[4:5]
	global_load_dwordx4 v[130:133], v[2:3], off
	global_load_dwordx4 v[134:137], v[2:3], off offset:32
	global_load_dwordx4 v[138:141], v[2:3], off offset:64
	global_load_dwordx4 v[142:145], v[2:3], off offset:96
	global_load_dwordx4 v[146:149], v[0:1], off
	global_load_dwordx4 v[150:153], v[0:1], off offset:32
	global_load_dwordx4 v[154:157], v[0:1], off offset:64
	global_load_dwordx4 v[158:161], v[0:1], off offset:96
	v_lshl_add_u64 v[214:215], v[210:211], 0, s[4:5]
	global_load_dwordx4 v[0:3], v[212:213], off
	global_load_dwordx4 v[4:7], v[214:215], off
	s_mov_b64 s[6:7], 0x2000
	v_lshl_add_u64 v[182:183], v[212:213], 0, s[6:7]
	global_load_dwordx4 v[182:185], v[182:183], off
	global_load_dwordx4 v[178:181], v[214:215], off offset:128
	v_mov_b32_e32 v82, 0xf149f2ca
	s_mov_b32 s4, 0
	s_movk_i32 s42, 0x6c00
	s_movk_i32 s41, 0x4800
	s_mov_b32 s5, 0x9000
	v_mov_b32_e32 v162, 0
	v_mov_b32_e32 v163, 0
	v_mov_b32_e32 v164, 0
	v_mov_b32_e32 v165, 0
	v_mov_b32_e32 v174, 0
	v_mov_b32_e32 v175, 0
	v_mov_b32_e32 v176, 0
	v_mov_b32_e32 v177, 0
	v_mov_b32_e32 v166, 0
	v_mov_b32_e32 v167, 0
	v_mov_b32_e32 v168, 0
	v_mov_b32_e32 v169, 0
	v_mov_b32_e32 v170, 0
	v_mov_b32_e32 v171, 0
	v_mov_b32_e32 v172, 0
	v_mov_b32_e32 v173, 0
	v_mov_b32_e32 v83, v82
	v_mov_b32_e32 v84, v82
	v_mov_b32_e32 v85, v82
	v_mov_b32_e32 v86, v82
	v_mov_b32_e32 v87, v82
	v_mov_b32_e32 v88, v82
	v_mov_b32_e32 v89, v82
	v_mov_b32_e32 v90, v82
	v_mov_b32_e32 v91, v82
	v_mov_b32_e32 v92, v82
	v_mov_b32_e32 v93, v82
	v_mov_b32_e32 v94, v82
	v_mov_b32_e32 v95, v82
	v_mov_b32_e32 v96, v82
	v_mov_b32_e32 v97, v82
	v_mov_b32_e32 v66, v82
	v_mov_b32_e32 v67, v82
	v_mov_b32_e32 v68, v82
	v_mov_b32_e32 v69, v82
	v_mov_b32_e32 v70, v82
	v_mov_b32_e32 v71, v82
	v_mov_b32_e32 v72, v82
	v_mov_b32_e32 v73, v82
	v_mov_b32_e32 v74, v82
	v_mov_b32_e32 v75, v82
	v_mov_b32_e32 v76, v82
	v_mov_b32_e32 v77, v82
	v_mov_b32_e32 v78, v82
	v_mov_b32_e32 v79, v82
	v_mov_b32_e32 v80, v82
	v_mov_b32_e32 v81, v82
	s_waitcnt vmcnt(3)
	ds_write_b128 v203, v[0:3]
	s_waitcnt vmcnt(2)
	ds_write_b128 v203, v[4:7] offset:18432
	v_mov_b32_e32 v0, 0
	v_mov_b32_e32 v1, v0
	v_mov_b32_e32 v2, v0
	v_mov_b32_e32 v3, v0
	v_mov_b32_e32 v4, v0
	v_mov_b32_e32 v5, v0
	v_mov_b32_e32 v6, v0
	v_mov_b32_e32 v7, v0
	v_mov_b32_e32 v8, v0
	v_mov_b32_e32 v9, v0
	v_mov_b32_e32 v10, v0
	v_mov_b32_e32 v11, v0
	v_mov_b32_e32 v12, v0
	v_mov_b32_e32 v13, v0
	v_mov_b32_e32 v14, v0
	v_mov_b32_e32 v15, v0
	v_mov_b32_e32 v16, v0
	v_mov_b32_e32 v17, v0
	v_mov_b32_e32 v18, v0
	v_mov_b32_e32 v19, v0
	v_mov_b32_e32 v20, v0
	v_mov_b32_e32 v21, v0
	v_mov_b32_e32 v22, v0
	v_mov_b32_e32 v23, v0
	v_mov_b32_e32 v24, v0
	v_mov_b32_e32 v25, v0
	v_mov_b32_e32 v26, v0
	v_mov_b32_e32 v27, v0
	v_mov_b32_e32 v28, v0
	v_mov_b32_e32 v29, v0
	v_mov_b32_e32 v30, v0
	v_mov_b32_e32 v31, v0
	v_mov_b32_e32 v34, v0
	v_mov_b32_e32 v35, v0
	v_mov_b32_e32 v36, v0
	v_mov_b32_e32 v37, v0
	v_mov_b32_e32 v38, v0
	v_mov_b32_e32 v39, v0
	v_mov_b32_e32 v40, v0
	v_mov_b32_e32 v41, v0
	v_mov_b32_e32 v42, v0
	v_mov_b32_e32 v43, v0
	v_mov_b32_e32 v44, v0
	v_mov_b32_e32 v45, v0
	v_mov_b32_e32 v46, v0
	v_mov_b32_e32 v47, v0
	v_mov_b32_e32 v48, v0
	v_mov_b32_e32 v49, v0
	v_mov_b32_e32 v50, v0
	v_mov_b32_e32 v51, v0
	v_mov_b32_e32 v52, v0
	v_mov_b32_e32 v53, v0
	v_mov_b32_e32 v54, v0
	v_mov_b32_e32 v55, v0
	v_mov_b32_e32 v56, v0
	v_mov_b32_e32 v57, v0
	v_mov_b32_e32 v58, v0
	v_mov_b32_e32 v59, v0
	v_mov_b32_e32 v60, v0
	v_mov_b32_e32 v61, v0
	v_mov_b32_e32 v62, v0
	v_mov_b32_e32 v63, v0
	v_mov_b32_e32 v64, v0
	v_mov_b32_e32 v65, v0
	v_mov_b32_e32 v216, v0
	v_mov_b32_e32 v217, v0
	s_waitcnt lgkmcnt(0)
	s_barrier
	v_mov_b32_e32 v234, v245
	v_add_u32_e32 v235, s5, v32
	s_cmpk_lt_u32 s38, 0x100
	s_cselect_b32 s101, 0, 1
	v_mov_b32_e32 v186, 0
	v_mov_b32_e32 v187, 0
	v_mov_b32_e32 v188, 0
	v_mov_b32_e32 v189, 0
	v_mov_b32_e32 v190, 0
	v_mov_b32_e32 v191, 0
	v_mov_b32_e32 v192, 0
	v_mov_b32_e32 v193, 0
	v_mov_b32_e32 v218, 0
	v_mov_b32_e32 v219, 0
	v_mov_b32_e32 v220, 0
	v_mov_b32_e32 v221, 0
	v_mov_b32_e32 v222, 0
	v_mov_b32_e32 v223, 0
	v_mov_b32_e32 v224, 0
	v_mov_b32_e32 v225, 0
	ds_read_b128 v[226:229], v235
	ds_read_b128 v[230:233], v235 offset:4608
	s_cmp_eq_u32 s101, 0
	s_cbranch_scc1 .Lpp_enter
	v_add_u32_e32 v198, 0x2400, v203
	v_add_u32_e32 v199, s42, v203
	s_waitcnt vmcnt(0)
	ds_write_b128 v199, v[178:181]
	ds_write_b128 v198, v[182:185]
	s_mov_b64 s[6:7], 0x4000
	v_lshl_add_u64 v[182:183], v[212:213], 0, s[6:7]
	global_load_dwordx4 v[182:185], v[182:183], off
	global_load_dwordx4 v[178:181], v[214:215], off offset:256
	s_waitcnt lgkmcnt(0)
	s_barrier
.Lpp_enter:
.LBB0_1013:
	s_waitcnt lgkmcnt(1)
	v_mfma_f32_32x32x16_bf16 v[50:65], v[226:229], v[170:173], v[50:65]
	ds_read_b128 v[246:249], v235 offset:32
	v_mfma_f32_32x32x16_bf16 v[16:31], v[226:229], v[174:177], v[16:31]
	s_waitcnt lgkmcnt(1)
	v_mfma_f32_32x32x16_bf16 v[34:49], v[230:233], v[170:173], v[34:49]
	ds_read_b128 v[226:229], v235 offset:4640
	v_mfma_f32_32x32x16_bf16 v[0:15], v[230:233], v[174:177], v[0:15]
	s_waitcnt lgkmcnt(1)
	v_mfma_f32_32x32x16_bf16 v[50:65], v[246:249], v[166:169], v[50:65]
	ds_read_b128 v[230:233], v235 offset:64
	v_mfma_f32_32x32x16_bf16 v[16:31], v[246:249], v[162:165], v[16:31]
	s_waitcnt lgkmcnt(1)
	v_mfma_f32_32x32x16_bf16 v[34:49], v[226:229], v[166:169], v[34:49]
	ds_read_b128 v[246:249], v235 offset:4672
	v_mfma_f32_32x32x16_bf16 v[0:15], v[226:229], v[162:165], v[0:15]
	s_waitcnt lgkmcnt(1)
	v_mfma_f32_32x32x16_bf16 v[50:65], v[230:233], v[186:189], v[50:65]
	ds_read_b128 v[226:229], v235 offset:96
	v_mfma_f32_32x32x16_bf16 v[16:31], v[230:233], v[218:221], v[16:31]
	s_waitcnt lgkmcnt(1)
	v_mfma_f32_32x32x16_bf16 v[34:49], v[246:249], v[186:189], v[34:49]
	ds_read_b128 v[230:233], v235 offset:4704
	v_mfma_f32_32x32x16_bf16 v[0:15], v[246:249], v[218:221], v[0:15]
	s_waitcnt lgkmcnt(1)
	v_mfma_f32_32x32x16_bf16 v[50:65], v[226:229], v[190:193], v[50:65]
	ds_read_b128 v[246:249], v234
	v_mfma_f32_32x32x16_bf16 v[16:31], v[226:229], v[222:225], v[16:31]
	s_waitcnt lgkmcnt(1)
	v_mfma_f32_32x32x16_bf16 v[34:49], v[230:233], v[190:193], v[34:49]
	ds_read_b128 v[226:229], v234 offset:32
	v_mfma_f32_32x32x16_bf16 v[0:15], v[230:233], v[222:225], v[0:15]
	s_waitcnt lgkmcnt(1)
	v_mfma_f32_32x32x16_bf16 v[114:129], v[246:249], v[130:133], 0
	ds_read_b128 v[230:233], v234 offset:64
	v_mfma_f32_32x32x16_bf16 v[98:113], v[246:249], v[146:149], 0
	s_waitcnt lgkmcnt(1)
	v_mfma_f32_32x32x16_bf16 v[114:129], v[226:229], v[134:137], v[114:129]
	ds_read_b128 v[246:249], v234 offset:96
	v_mfma_f32_32x32x16_bf16 v[98:113], v[226:229], v[150:153], v[98:113]
	s_waitcnt lgkmcnt(1)
	v_mfma_f32_32x32x16_bf16 v[114:129], v[230:233], v[138:141], v[114:129]
	ds_read_b128 v[226:229], v234 offset:4608
	v_mfma_f32_32x32x16_bf16 v[98:113], v[230:233], v[154:157], v[98:113]
	s_waitcnt lgkmcnt(1)
	v_mfma_f32_32x32x16_bf16 v[114:129], v[246:249], v[142:145], v[114:129]
	ds_read_b128 v[230:233], v234 offset:4640
	v_mfma_f32_32x32x16_bf16 v[98:113], v[246:249], v[158:161], v[98:113]
	s_waitcnt lgkmcnt(1)
	v_mfma_f32_32x32x16_bf16 v[82:97], v[226:229], v[130:133], 0
	ds_read_b128 v[246:249], v234 offset:4672
	v_mfma_f32_32x32x16_bf16 v[66:81], v[226:229], v[146:149], 0
	s_waitcnt lgkmcnt(1)
	v_mfma_f32_32x32x16_bf16 v[82:97], v[230:233], v[134:137], v[82:97]
	ds_read_b128 v[226:229], v234 offset:4704
	v_mfma_f32_32x32x16_bf16 v[66:81], v[230:233], v[150:153], v[66:81]
	s_waitcnt lgkmcnt(1)
	v_mfma_f32_32x32x16_bf16 v[82:97], v[246:249], v[138:141], v[82:97]
	v_mfma_f32_32x32x16_bf16 v[66:81], v[246:249], v[154:157], v[66:81]
	s_waitcnt lgkmcnt(0)
	v_mfma_f32_32x32x16_bf16 v[82:97], v[226:229], v[142:145], v[82:97]
	v_mfma_f32_32x32x16_bf16 v[66:81], v[226:229], v[158:161], v[66:81]
	s_barrier
	s_add_i32 s44, s4, 1
	s_add_i32 s43, s44, s101
	s_and_b32 s43, s43, 1
	s_mul_i32 s43, s43, 0x2400
	s_cmp_eq_u32 s101, 0
	s_cselect_b32 s6, s42, s5
	v_add_u32_e32 v198, s43, v203
	v_add_u32_e32 v199, s6, v203
	s_add_i32 s16, s44, s101
	s_add_i32 s16, s16, 1
	s_min_u32 s16, s16, 63
	s_waitcnt vmcnt(0)
	ds_write_b128 v199, v[178:181]
	ds_write_b128 v198, v[182:185]
	s_lshl_b64 s[6:7], s[16:17], 13
	v_lshl_add_u64 v[182:183], v[212:213], 0, s[6:7]
	s_lshl_b64 s[6:7], s[16:17], 7
	global_load_dwordx4 v[182:185], v[182:183], off
	v_lshl_add_u64 v[178:179], v[214:215], 0, s[6:7]
	s_and_b32 s43, s44, 1
	global_load_dwordx4 v[178:181], v[178:179], off
	s_mul_i32 s43, s43, 0x2400
	v_exp_f32_e32 v114, v114
	v_exp_f32_e32 v115, v115
	v_exp_f32_e32 v116, v116
	v_exp_f32_e32 v117, v117
	v_exp_f32_e32 v118, v118
	v_exp_f32_e32 v119, v119
	v_exp_f32_e32 v120, v120
	v_exp_f32_e32 v121, v121
	v_cvt_pk_bf16_f32 v170, v114, v115
	v_add_f32_e32 v114, v114, v115
	v_exp_f32_e32 v122, v122
	v_exp_f32_e32 v123, v123
	v_cvt_pk_bf16_f32 v171, v116, v117
	v_add_f32_e32 v116, v116, v117
	v_add_f32_e32 v217, v217, v114
	v_exp_f32_e32 v124, v124
	v_exp_f32_e32 v125, v125
	v_cvt_pk_bf16_f32 v172, v118, v119
	v_add_f32_e32 v118, v118, v119
	v_add_f32_e32 v217, v217, v116
	v_exp_f32_e32 v126, v126
	v_exp_f32_e32 v127, v127
	v_cvt_pk_bf16_f32 v173, v120, v121
	v_add_f32_e32 v120, v120, v121
	v_add_f32_e32 v217, v217, v118
	v_exp_f32_e32 v128, v128
	v_exp_f32_e32 v129, v129
	v_cvt_pk_bf16_f32 v166, v122, v123
	v_add_f32_e32 v122, v122, v123
	v_add_f32_e32 v217, v217, v120
	v_exp_f32_e32 v98, v98
	v_exp_f32_e32 v99, v99
	v_cvt_pk_bf16_f32 v167, v124, v125
	v_add_f32_e32 v124, v124, v125
	v_add_f32_e32 v217, v217, v122
	v_exp_f32_e32 v100, v100
	v_exp_f32_e32 v101, v101
	v_cvt_pk_bf16_f32 v168, v126, v127
	v_add_f32_e32 v126, v126, v127
	v_add_f32_e32 v217, v217, v124
	v_exp_f32_e32 v102, v102
	v_exp_f32_e32 v103, v103
	v_cvt_pk_bf16_f32 v169, v128, v129
	v_add_f32_e32 v128, v128, v129
	v_add_f32_e32 v217, v217, v126
	v_exp_f32_e32 v104, v104
	v_exp_f32_e32 v105, v105
	v_cvt_pk_bf16_f32 v174, v98, v99
	v_add_f32_e32 v98, v98, v99
	v_add_f32_e32 v217, v217, v128
	v_exp_f32_e32 v106, v106
	v_exp_f32_e32 v107, v107
	v_cvt_pk_bf16_f32 v175, v100, v101
	v_add_f32_e32 v100, v100, v101
	v_add_f32_e32 v216, v216, v98
	v_exp_f32_e32 v108, v108
	v_exp_f32_e32 v109, v109
	v_cvt_pk_bf16_f32 v176, v102, v103
	v_add_f32_e32 v102, v102, v103
	v_add_f32_e32 v216, v216, v100
	v_exp_f32_e32 v110, v110
	v_exp_f32_e32 v111, v111
	v_cvt_pk_bf16_f32 v177, v104, v105
	v_add_f32_e32 v104, v104, v105
	v_add_f32_e32 v216, v216, v102
	v_exp_f32_e32 v112, v112
	v_exp_f32_e32 v113, v113
	v_cvt_pk_bf16_f32 v162, v106, v107
	v_add_f32_e32 v106, v106, v107
	v_add_f32_e32 v216, v216, v104
	v_cvt_pk_bf16_f32 v163, v108, v109
	v_add_f32_e32 v108, v108, v109
	v_add_f32_e32 v216, v216, v106
	v_cvt_pk_bf16_f32 v164, v110, v111
	v_add_f32_e32 v110, v110, v111
	v_add_f32_e32 v216, v216, v108
	v_cvt_pk_bf16_f32 v165, v112, v113
	v_add_f32_e32 v112, v112, v113
	v_add_f32_e32 v216, v216, v110
	v_add_f32_e32 v216, v216, v112
	v_exp_f32_e32 v82, v82
	v_exp_f32_e32 v83, v83
	v_exp_f32_e32 v84, v84
	v_exp_f32_e32 v85, v85
	v_exp_f32_e32 v86, v86
	v_exp_f32_e32 v87, v87
	v_exp_f32_e32 v88, v88
	v_exp_f32_e32 v89, v89
	v_cvt_pk_bf16_f32 v186, v82, v83
	v_add_f32_e32 v82, v82, v83
	v_exp_f32_e32 v90, v90
	v_exp_f32_e32 v91, v91
	v_cvt_pk_bf16_f32 v187, v84, v85
	v_add_f32_e32 v84, v84, v85
	v_add_f32_e32 v217, v217, v82
	v_exp_f32_e32 v92, v92
	v_exp_f32_e32 v93, v93
	v_cvt_pk_bf16_f32 v188, v86, v87
	v_add_f32_e32 v86, v86, v87
	v_add_f32_e32 v217, v217, v84
	v_exp_f32_e32 v94, v94
	v_exp_f32_e32 v95, v95
	v_cvt_pk_bf16_f32 v189, v88, v89
	v_add_f32_e32 v88, v88, v89
	v_add_f32_e32 v217, v217, v86
	v_exp_f32_e32 v96, v96
	v_exp_f32_e32 v97, v97
	v_cvt_pk_bf16_f32 v190, v90, v91
	v_add_f32_e32 v90, v90, v91
	v_add_f32_e32 v217, v217, v88
	v_exp_f32_e32 v66, v66
	v_exp_f32_e32 v67, v67
	v_cvt_pk_bf16_f32 v191, v92, v93
	v_add_f32_e32 v92, v92, v93
	v_add_f32_e32 v217, v217, v90
	v_exp_f32_e32 v68, v68
	v_exp_f32_e32 v69, v69
	v_cvt_pk_bf16_f32 v192, v94, v95
	v_add_f32_e32 v94, v94, v95
	v_add_f32_e32 v217, v217, v92
	v_exp_f32_e32 v70, v70
	v_exp_f32_e32 v71, v71
	v_cvt_pk_bf16_f32 v193, v96, v97
	v_add_f32_e32 v96, v96, v97
	v_add_f32_e32 v217, v217, v94
	v_exp_f32_e32 v72, v72
	v_exp_f32_e32 v73, v73
	v_cvt_pk_bf16_f32 v218, v66, v67
	v_add_f32_e32 v66, v66, v67
	v_add_f32_e32 v217, v217, v96
	v_exp_f32_e32 v74, v74
	v_exp_f32_e32 v75, v75
	v_cvt_pk_bf16_f32 v219, v68, v69
	v_add_f32_e32 v68, v68, v69
	v_add_f32_e32 v216, v216, v66
	v_exp_f32_e32 v76, v76
	v_exp_f32_e32 v77, v77
	v_cvt_pk_bf16_f32 v220, v70, v71
	v_add_f32_e32 v70, v70, v71
	v_add_f32_e32 v216, v216, v68
	v_exp_f32_e32 v78, v78
	v_exp_f32_e32 v79, v79
	v_cvt_pk_bf16_f32 v221, v72, v73
	v_add_f32_e32 v72, v72, v73
	v_add_f32_e32 v216, v216, v70
	v_exp_f32_e32 v80, v80
	v_exp_f32_e32 v81, v81
	v_cvt_pk_bf16_f32 v222, v74, v75
	v_add_f32_e32 v74, v74, v75
	v_add_f32_e32 v216, v216, v72
	v_cvt_pk_bf16_f32 v223, v76, v77
	v_add_f32_e32 v76, v76, v77
	v_add_f32_e32 v216, v216, v74
	v_cvt_pk_bf16_f32 v224, v78, v79
	v_add_f32_e32 v78, v78, v79
	v_add_f32_e32 v216, v216, v76
	v_cvt_pk_bf16_f32 v225, v80, v81
	v_add_f32_e32 v80, v80, v81
	v_add_f32_e32 v216, v216, v78
	v_add_f32_e32 v216, v216, v80
	v_add_u32_e32 v235, s41, v32
	v_add_u32_e32 v234, s43, v245
	ds_read_b128 v[226:229], v235
	ds_read_b128 v[230:233], v235 offset:4608
	s_waitcnt lgkmcnt(2)
	s_mov_b32 s6, s5
	s_mov_b32 s5, s41
	s_mov_b32 s41, s42
	s_mov_b32 s42, s6
	s_mov_b32 s4, s44
	s_cmp_eq_u32 s44, 63
	s_barrier
	s_cbranch_scc0 .LBB0_1013
	s_waitcnt lgkmcnt(1)
	v_mfma_f32_32x32x16_bf16 v[50:65], v[226:229], v[170:173], v[50:65]
	ds_read_b128 v[246:249], v235 offset:32
	v_mfma_f32_32x32x16_bf16 v[16:31], v[226:229], v[174:177], v[16:31]
	s_waitcnt lgkmcnt(1)
	v_mfma_f32_32x32x16_bf16 v[34:49], v[230:233], v[170:173], v[34:49]
	ds_read_b128 v[226:229], v235 offset:4640
	v_mfma_f32_32x32x16_bf16 v[0:15], v[230:233], v[174:177], v[0:15]
	s_waitcnt lgkmcnt(1)
	v_mfma_f32_32x32x16_bf16 v[50:65], v[246:249], v[166:169], v[50:65]
	ds_read_b128 v[230:233], v235 offset:64
	v_mfma_f32_32x32x16_bf16 v[16:31], v[246:249], v[162:165], v[16:31]
	s_waitcnt lgkmcnt(1)
	v_mfma_f32_32x32x16_bf16 v[34:49], v[226:229], v[166:169], v[34:49]
	ds_read_b128 v[246:249], v235 offset:4672
	v_mfma_f32_32x32x16_bf16 v[0:15], v[226:229], v[162:165], v[0:15]
	s_waitcnt lgkmcnt(1)
	v_mfma_f32_32x32x16_bf16 v[50:65], v[230:233], v[186:189], v[50:65]
	ds_read_b128 v[226:229], v235 offset:96
	v_mfma_f32_32x32x16_bf16 v[16:31], v[230:233], v[218:221], v[16:31]
	s_waitcnt lgkmcnt(1)
	v_mfma_f32_32x32x16_bf16 v[34:49], v[246:249], v[186:189], v[34:49]
	ds_read_b128 v[230:233], v235 offset:4704
	v_mfma_f32_32x32x16_bf16 v[0:15], v[246:249], v[218:221], v[0:15]
	s_waitcnt lgkmcnt(1)
	v_mfma_f32_32x32x16_bf16 v[50:65], v[226:229], v[190:193], v[50:65]
	ds_read_b128 v[246:249], v234
	v_mfma_f32_32x32x16_bf16 v[16:31], v[226:229], v[222:225], v[16:31]
	s_waitcnt lgkmcnt(1)
	v_mfma_f32_32x32x16_bf16 v[34:49], v[230:233], v[190:193], v[34:49]
	ds_read_b128 v[226:229], v234 offset:32
	v_mfma_f32_32x32x16_bf16 v[0:15], v[230:233], v[222:225], v[0:15]
	s_waitcnt lgkmcnt(1)
	v_mfma_f32_32x32x16_bf16 v[114:129], v[246:249], v[130:133], 0
	ds_read_b128 v[230:233], v234 offset:64
	v_mfma_f32_32x32x16_bf16 v[98:113], v[246:249], v[146:149], 0
	s_waitcnt lgkmcnt(1)
	v_mfma_f32_32x32x16_bf16 v[114:129], v[226:229], v[134:137], v[114:129]
	ds_read_b128 v[246:249], v234 offset:96
	v_mfma_f32_32x32x16_bf16 v[98:113], v[226:229], v[150:153], v[98:113]
	s_waitcnt lgkmcnt(1)
	v_mfma_f32_32x32x16_bf16 v[114:129], v[230:233], v[138:141], v[114:129]
	ds_read_b128 v[226:229], v234 offset:4608
	v_mfma_f32_32x32x16_bf16 v[98:113], v[230:233], v[154:157], v[98:113]
	s_waitcnt lgkmcnt(1)
	v_mfma_f32_32x32x16_bf16 v[114:129], v[246:249], v[142:145], v[114:129]
	ds_read_b128 v[230:233], v234 offset:4640
	v_mfma_f32_32x32x16_bf16 v[98:113], v[246:249], v[158:161], v[98:113]
	s_waitcnt lgkmcnt(1)
	v_mfma_f32_32x32x16_bf16 v[82:97], v[226:229], v[130:133], 0
	ds_read_b128 v[246:249], v234 offset:4672
	v_mfma_f32_32x32x16_bf16 v[66:81], v[226:229], v[146:149], 0
	s_waitcnt lgkmcnt(1)
	v_mfma_f32_32x32x16_bf16 v[82:97], v[230:233], v[134:137], v[82:97]
	ds_read_b128 v[226:229], v234 offset:4704
	v_mfma_f32_32x32x16_bf16 v[66:81], v[230:233], v[150:153], v[66:81]
	s_waitcnt lgkmcnt(1)
	v_mfma_f32_32x32x16_bf16 v[82:97], v[246:249], v[138:141], v[82:97]
	v_mfma_f32_32x32x16_bf16 v[66:81], v[246:249], v[154:157], v[66:81]
	s_waitcnt lgkmcnt(0)
	v_mfma_f32_32x32x16_bf16 v[82:97], v[226:229], v[142:145], v[82:97]
	v_mfma_f32_32x32x16_bf16 v[66:81], v[226:229], v[158:161], v[66:81]
	s_barrier
	v_exp_f32_e32 v114, v114
	v_exp_f32_e32 v115, v115
	v_exp_f32_e32 v116, v116
	v_exp_f32_e32 v117, v117
	v_exp_f32_e32 v118, v118
	v_exp_f32_e32 v119, v119
	v_exp_f32_e32 v120, v120
	v_exp_f32_e32 v121, v121
	v_cvt_pk_bf16_f32 v170, v114, v115
	v_add_f32_e32 v114, v114, v115
	v_exp_f32_e32 v122, v122
	v_exp_f32_e32 v123, v123
	v_cvt_pk_bf16_f32 v171, v116, v117
	v_add_f32_e32 v116, v116, v117
	v_add_f32_e32 v217, v217, v114
	v_exp_f32_e32 v124, v124
	v_exp_f32_e32 v125, v125
	v_cvt_pk_bf16_f32 v172, v118, v119
	v_add_f32_e32 v118, v118, v119
	v_add_f32_e32 v217, v217, v116
	v_exp_f32_e32 v126, v126
	v_exp_f32_e32 v127, v127
	v_cvt_pk_bf16_f32 v173, v120, v121
	v_add_f32_e32 v120, v120, v121
	v_add_f32_e32 v217, v217, v118
	v_exp_f32_e32 v128, v128
	v_exp_f32_e32 v129, v129
	v_cvt_pk_bf16_f32 v166, v122, v123
	v_add_f32_e32 v122, v122, v123
	v_add_f32_e32 v217, v217, v120
	v_exp_f32_e32 v98, v98
	v_exp_f32_e32 v99, v99
	v_cvt_pk_bf16_f32 v167, v124, v125
	v_add_f32_e32 v124, v124, v125
	v_add_f32_e32 v217, v217, v122
	v_exp_f32_e32 v100, v100
	v_exp_f32_e32 v101, v101
	v_cvt_pk_bf16_f32 v168, v126, v127
	v_add_f32_e32 v126, v126, v127
	v_add_f32_e32 v217, v217, v124
	v_exp_f32_e32 v102, v102
	v_exp_f32_e32 v103, v103
	v_cvt_pk_bf16_f32 v169, v128, v129
	v_add_f32_e32 v128, v128, v129
	v_add_f32_e32 v217, v217, v126
	v_exp_f32_e32 v104, v104
	v_exp_f32_e32 v105, v105
	v_cvt_pk_bf16_f32 v174, v98, v99
	v_add_f32_e32 v98, v98, v99
	v_add_f32_e32 v217, v217, v128
	v_exp_f32_e32 v106, v106
	v_exp_f32_e32 v107, v107
	v_cvt_pk_bf16_f32 v175, v100, v101
	v_add_f32_e32 v100, v100, v101
	v_add_f32_e32 v216, v216, v98
	v_exp_f32_e32 v108, v108
	v_exp_f32_e32 v109, v109
	v_cvt_pk_bf16_f32 v176, v102, v103
	v_add_f32_e32 v102, v102, v103
	v_add_f32_e32 v216, v216, v100
	v_exp_f32_e32 v110, v110
	v_exp_f32_e32 v111, v111
	v_cvt_pk_bf16_f32 v177, v104, v105
	v_add_f32_e32 v104, v104, v105
	v_add_f32_e32 v216, v216, v102
	v_exp_f32_e32 v112, v112
	v_exp_f32_e32 v113, v113
	v_cvt_pk_bf16_f32 v162, v106, v107
	v_add_f32_e32 v106, v106, v107
	v_add_f32_e32 v216, v216, v104
	v_cvt_pk_bf16_f32 v163, v108, v109
	v_add_f32_e32 v108, v108, v109
	v_add_f32_e32 v216, v216, v106
	v_cvt_pk_bf16_f32 v164, v110, v111
	v_add_f32_e32 v110, v110, v111
	v_add_f32_e32 v216, v216, v108
	v_cvt_pk_bf16_f32 v165, v112, v113
	v_add_f32_e32 v112, v112, v113
	v_add_f32_e32 v216, v216, v110
	v_add_f32_e32 v216, v216, v112
	s_waitcnt vmcnt(0)
	s_barrier
	s_cmp_eq_u32 s101, 0
	s_cbranch_scc0 .Lpp_exit
	s_barrier
.Lpp_exit:
	v_exp_f32_e32 v82, v82
	v_exp_f32_e32 v83, v83
	v_exp_f32_e32 v84, v84
	v_exp_f32_e32 v85, v85
	v_add_f32_e32 v98, 0, v82
	v_exp_f32_e32 v99, v86
	v_add_f32_e32 v98, v83, v98
	v_add_f32_e32 v98, v84, v98
	v_add_f32_e32 v98, v85, v98
	v_add_f32_e32 v86, v99, v98
	v_exp_f32_e32 v98, v87
	v_exp_f32_e32 v100, v88
	v_exp_f32_e32 v89, v89
	v_exp_f32_e32 v101, v90
	v_add_f32_e32 v86, v98, v86
	v_exp_f32_e32 v91, v91
	v_add_f32_e32 v86, v100, v86
	v_exp_f32_e32 v92, v92
	v_add_f32_e32 v86, v89, v86
	v_exp_f32_e32 v93, v93
	v_add_f32_e32 v86, v101, v86
	v_exp_f32_e32 v94, v94
	v_add_f32_e32 v86, v91, v86
	v_exp_f32_e32 v95, v95
	v_add_f32_e32 v86, v92, v86
	v_exp_f32_e32 v96, v96
	v_add_f32_e32 v86, v93, v86
	v_exp_f32_e32 v97, v97
	v_add_f32_e32 v86, v94, v86
	v_exp_f32_e32 v66, v66
	v_add_f32_e32 v86, v95, v86
	v_exp_f32_e32 v67, v67
	v_add_f32_e32 v86, v96, v86
	v_exp_f32_e32 v68, v68
	v_add_f32_e32 v86, v97, v86
	v_exp_f32_e32 v69, v69
	v_add_f32_e32 v90, v217, v86
	v_cvt_pk_bf16_f32 v86, v82, v83
	v_cvt_pk_bf16_f32 v82, v101, v91
	v_cvt_pk_bf16_f32 v83, v92, v93
	v_add_f32_e32 v91, 0, v66
	v_exp_f32_e32 v92, v70
	v_add_f32_e32 v91, v67, v91
	v_add_f32_e32 v91, v68, v91
	v_add_f32_e32 v91, v69, v91
	v_add_f32_e32 v70, v92, v91
	v_exp_f32_e32 v91, v71
	v_exp_f32_e32 v93, v72
	v_exp_f32_e32 v73, v73
	v_cvt_pk_bf16_f32 v87, v84, v85
	v_cvt_pk_bf16_f32 v84, v94, v95
	v_exp_f32_e32 v94, v74
	v_add_f32_e32 v70, v91, v70
	v_exp_f32_e32 v75, v75
	v_add_f32_e32 v70, v93, v70
	v_exp_f32_e32 v76, v76
	v_add_f32_e32 v70, v73, v70
	v_exp_f32_e32 v77, v77
	v_add_f32_e32 v70, v94, v70
	v_exp_f32_e32 v78, v78
	v_add_f32_e32 v70, v75, v70
	v_exp_f32_e32 v79, v79
	v_add_f32_e32 v70, v76, v70
	v_exp_f32_e32 v80, v80
	v_add_f32_e32 v70, v77, v70
	v_exp_f32_e32 v81, v81
	v_add_f32_e32 v70, v78, v70
	v_add_f32_e32 v70, v79, v70
	v_add_f32_e32 v70, v80, v70
	v_add_f32_e32 v70, v81, v70
	v_add_f32_e32 v74, v216, v70
	v_cvt_pk_bf16_f32 v70, v66, v67
	v_cvt_pk_bf16_f32 v71, v68, v69
	v_cvt_pk_bf16_f32 v72, v92, v91
	v_cvt_pk_bf16_f32 v73, v93, v73
	v_cvt_pk_bf16_f32 v66, v94, v75
	v_cvt_pk_bf16_f32 v67, v76, v77
	v_cvt_pk_bf16_f32 v68, v78, v79
	ds_read_b128 v[76:79], v32 offset:18432
	ds_read_b128 v[92:95], v32 offset:18464
	s_waitcnt lgkmcnt(1)
	v_mfma_f32_32x32x16_bf16 v[50:65], v[76:79], v[170:173], v[50:65]
	v_cvt_pk_bf16_f32 v88, v99, v98
	v_cvt_pk_bf16_f32 v89, v100, v89
	v_cvt_pk_bf16_f32 v85, v96, v97
	v_cvt_pk_bf16_f32 v69, v80, v81
	s_lshl_b32 s4, s39, 12
	s_add_i32 s40, s40, s4
	s_lshl_b32 s16, s1, 7
	v_mfma_f32_32x32x16_bf16 v[16:31], v[76:79], v[174:177], v[16:31]
	ds_read_b128 v[76:79], v32 offset:23040
	s_add_i32 s0, s0, s78
	s_cmpk_gt_i32 s0, 0x3ff
	s_waitcnt lgkmcnt(0)
	v_mfma_f32_32x32x16_bf16 v[34:49], v[76:79], v[170:173], v[34:49]
	v_mfma_f32_32x32x16_bf16 v[0:15], v[76:79], v[174:177], v[0:15]
	ds_read_b128 v[76:79], v32 offset:23072
	s_waitcnt lgkmcnt(0)
	v_mfma_f32_32x32x16_bf16 v[34:49], v[76:79], v[166:169], v[34:49]
	v_mfma_f32_32x32x16_bf16 v[0:15], v[76:79], v[162:165], v[0:15]
	ds_read_b128 v[76:79], v32 offset:18496
	v_mfma_f32_32x32x16_bf16 v[50:65], v[92:95], v[166:169], v[50:65]
	v_mfma_f32_32x32x16_bf16 v[16:31], v[92:95], v[162:165], v[16:31]
	s_waitcnt lgkmcnt(0)
	v_mfma_f32_32x32x16_bf16 v[50:65], v[76:79], v[86:89], v[50:65]
	v_mfma_f32_32x32x16_bf16 v[16:31], v[76:79], v[70:73], v[16:31]
	ds_read_b128 v[76:79], v32 offset:23104
	s_waitcnt lgkmcnt(0)
	v_mfma_f32_32x32x16_bf16 v[0:15], v[76:79], v[70:73], v[0:15]
	ds_read_b128 v[70:73], v32 offset:18528
	s_waitcnt lgkmcnt(0)
	v_mfma_f32_32x32x16_bf16 v[50:65], v[70:73], v[82:85], v[50:65]
	v_mfma_f32_32x32x16_bf16 v[16:31], v[70:73], v[66:69], v[16:31]
	ds_read_b128 v[70:73], v32 offset:23136
	s_waitcnt lgkmcnt(0)
	s_barrier
	v_mfma_f32_32x32x16_bf16 v[34:49], v[76:79], v[86:89], v[34:49]
	v_mfma_f32_32x32x16_bf16 v[0:15], v[70:73], v[66:69], v[0:15]
	ds_bpermute_b32 v69, v244, v90
	v_or_b32_e32 v68, s40, v202
	v_lshl_add_u64 v[66:67], v[206:207], 0, s[16:17]
	s_waitcnt lgkmcnt(0)
	v_add_f32_e32 v69, v90, v69
	v_mfma_f32_32x32x16_bf16 v[34:49], v[70:73], v[82:85], v[34:49]
	v_div_scale_f32 v70, s[4:5], v69, v69, 1.0
	v_rcp_f32_e32 v71, v70
	s_nop 0
	v_fma_f32 v72, -v70, v71, 1.0
	v_fmac_f32_e32 v71, v72, v71
	v_div_scale_f32 v72, vcc, 1.0, v69, 1.0
	v_mul_f32_e32 v73, v72, v71
	v_fma_f32 v75, -v70, v73, v72
	v_fmac_f32_e32 v73, v75, v71
	v_fma_f32 v70, -v70, v73, v72
	v_div_fmas_f32 v70, v70, v71, v73
	v_div_fixup_f32 v70, v70, v69, 1.0
	v_ashrrev_i32_e32 v69, 31, v68
	v_lshlrev_b64 v[72:73], 11, v[68:69]
	v_pk_mul_f32 v[34:35], v[34:35], v[70:71] op_sel_hi:[1,0]
	v_pk_mul_f32 v[36:37], v[36:37], v[70:71] op_sel_hi:[1,0]
	v_lshl_add_u64 v[72:73], v[66:67], 0, v[72:73]
	v_cvt_pk_bf16_f32 v34, v34, v35
	v_cvt_pk_bf16_f32 v35, v36, v37
	global_store_dwordx2 v[72:73], v[34:35], off offset:64
	v_pk_mul_f32 v[34:35], v[38:39], v[70:71] op_sel_hi:[1,0]
	v_pk_mul_f32 v[36:37], v[40:41], v[70:71] op_sel_hi:[1,0]
	v_cvt_pk_bf16_f32 v34, v34, v35
	v_cvt_pk_bf16_f32 v35, v36, v37
	global_store_dwordx2 v[72:73], v[34:35], off offset:80
	v_pk_mul_f32 v[34:35], v[42:43], v[70:71] op_sel_hi:[1,0]
	v_pk_mul_f32 v[36:37], v[44:45], v[70:71] op_sel_hi:[1,0]
	v_cvt_pk_bf16_f32 v34, v34, v35
	v_cvt_pk_bf16_f32 v35, v36, v37
	global_store_dwordx2 v[72:73], v[34:35], off offset:96
	v_pk_mul_f32 v[34:35], v[46:47], v[70:71] op_sel_hi:[1,0]
	v_pk_mul_f32 v[36:37], v[48:49], v[70:71] op_sel_hi:[1,0]
	v_cvt_pk_bf16_f32 v34, v34, v35
	v_cvt_pk_bf16_f32 v35, v36, v37
	global_store_dwordx2 v[72:73], v[34:35], off offset:112
	ds_bpermute_b32 v34, v244, v74
	v_pk_mul_f32 v[50:51], v[50:51], v[70:71] op_sel_hi:[1,0]
	v_pk_mul_f32 v[52:53], v[52:53], v[70:71] op_sel_hi:[1,0]
	v_cvt_pk_bf16_f32 v50, v50, v51
	v_cvt_pk_bf16_f32 v51, v52, v53
	s_waitcnt lgkmcnt(0)
	v_add_f32_e32 v34, v74, v34
	v_div_scale_f32 v35, s[4:5], v34, v34, 1.0
	v_rcp_f32_e32 v36, v35
	global_store_dwordx2 v[72:73], v[50:51], off
	v_pk_mul_f32 v[50:51], v[54:55], v[70:71] op_sel_hi:[1,0]
	v_pk_mul_f32 v[52:53], v[56:57], v[70:71] op_sel_hi:[1,0]
	v_fma_f32 v37, -v35, v36, 1.0
	v_fmac_f32_e32 v36, v37, v36
	v_div_scale_f32 v37, vcc, 1.0, v34, 1.0
	v_mul_f32_e32 v38, v37, v36
	v_fma_f32 v39, -v35, v38, v37
	v_fmac_f32_e32 v38, v39, v36
	v_fma_f32 v35, -v35, v38, v37
	v_div_fmas_f32 v35, v35, v36, v38
	v_or_b32_e32 v36, 32, v68
	v_div_fixup_f32 v34, v35, v34, 1.0
	v_ashrrev_i32_e32 v37, 31, v36
	v_lshlrev_b64 v[36:37], 11, v[36:37]
	v_pk_mul_f32 v[16:17], v[16:17], v[34:35] op_sel_hi:[1,0]
	v_pk_mul_f32 v[18:19], v[18:19], v[34:35] op_sel_hi:[1,0]
	v_pk_mul_f32 v[0:1], v[0:1], v[34:35] op_sel_hi:[1,0]
	v_pk_mul_f32 v[2:3], v[2:3], v[34:35] op_sel_hi:[1,0]
	v_lshl_add_u64 v[36:37], v[66:67], 0, v[36:37]
	v_cvt_pk_bf16_f32 v16, v16, v17
	v_cvt_pk_bf16_f32 v17, v18, v19
	v_cvt_pk_bf16_f32 v0, v0, v1
	v_cvt_pk_bf16_f32 v1, v2, v3
	global_store_dwordx2 v[36:37], v[16:17], off
	v_pk_mul_f32 v[16:17], v[20:21], v[34:35] op_sel_hi:[1,0]
	v_pk_mul_f32 v[18:19], v[22:23], v[34:35] op_sel_hi:[1,0]
	global_store_dwordx2 v[36:37], v[0:1], off offset:64
	v_pk_mul_f32 v[0:1], v[4:5], v[34:35] op_sel_hi:[1,0]
	v_pk_mul_f32 v[2:3], v[6:7], v[34:35] op_sel_hi:[1,0]
	v_cvt_pk_bf16_f32 v50, v50, v51
	v_cvt_pk_bf16_f32 v51, v52, v53
	v_cvt_pk_bf16_f32 v16, v16, v17
	v_cvt_pk_bf16_f32 v17, v18, v19
	v_cvt_pk_bf16_f32 v0, v0, v1
	v_cvt_pk_bf16_f32 v1, v2, v3
	global_store_dwordx2 v[72:73], v[50:51], off offset:16
	v_pk_mul_f32 v[50:51], v[58:59], v[70:71] op_sel_hi:[1,0]
	v_pk_mul_f32 v[52:53], v[60:61], v[70:71] op_sel_hi:[1,0]
	global_store_dwordx2 v[36:37], v[16:17], off offset:16
	v_pk_mul_f32 v[16:17], v[24:25], v[34:35] op_sel_hi:[1,0]
	v_pk_mul_f32 v[18:19], v[26:27], v[34:35] op_sel_hi:[1,0]
	global_store_dwordx2 v[36:37], v[0:1], off offset:80
	v_pk_mul_f32 v[0:1], v[8:9], v[34:35] op_sel_hi:[1,0]
	v_pk_mul_f32 v[2:3], v[10:11], v[34:35] op_sel_hi:[1,0]
	v_cvt_pk_bf16_f32 v50, v50, v51
	v_cvt_pk_bf16_f32 v51, v52, v53
	v_cvt_pk_bf16_f32 v16, v16, v17
	v_cvt_pk_bf16_f32 v17, v18, v19
	v_cvt_pk_bf16_f32 v0, v0, v1
	v_cvt_pk_bf16_f32 v1, v2, v3
	global_store_dwordx2 v[72:73], v[50:51], off offset:32
	v_pk_mul_f32 v[50:51], v[62:63], v[70:71] op_sel_hi:[1,0]
	v_pk_mul_f32 v[52:53], v[64:65], v[70:71] op_sel_hi:[1,0]
	global_store_dwordx2 v[36:37], v[16:17], off offset:32
	v_pk_mul_f32 v[16:17], v[28:29], v[34:35] op_sel_hi:[1,0]
	v_pk_mul_f32 v[18:19], v[30:31], v[34:35] op_sel_hi:[1,0]
	global_store_dwordx2 v[36:37], v[0:1], off offset:96
	v_pk_mul_f32 v[0:1], v[12:13], v[34:35] op_sel_hi:[1,0]
	v_pk_mul_f32 v[2:3], v[14:15], v[34:35] op_sel_hi:[1,0]
	v_cvt_pk_bf16_f32 v50, v50, v51
	v_cvt_pk_bf16_f32 v51, v52, v53
	v_cvt_pk_bf16_f32 v16, v16, v17
	v_cvt_pk_bf16_f32 v17, v18, v19
	v_cvt_pk_bf16_f32 v0, v0, v1
	v_cvt_pk_bf16_f32 v1, v2, v3
	global_store_dwordx2 v[72:73], v[50:51], off offset:48
	global_store_dwordx2 v[36:37], v[16:17], off offset:48
	global_store_dwordx2 v[36:37], v[0:1], off offset:112
	s_cbranch_scc0 .LBB0_1012
	v_mov_b32_e32 v246, 0x60
	v_mov_b64_e32 v[248:249], 0x300
	v_mov_b64_e32 v[250:251], 0x2ff

	.amdhsa_kernel _Z10fwd_kernel6Params
		.amdhsa_group_segment_fixed_size 0
		.amdhsa_private_segment_fixed_size 0
		.amdhsa_kernarg_size 392
		.amdhsa_user_sgpr_count 2
		.amdhsa_user_sgpr_dispatch_ptr 0
		.amdhsa_user_sgpr_queue_ptr 0
		.amdhsa_user_sgpr_kernarg_segment_ptr 1
		.amdhsa_user_sgpr_dispatch_id 0
		.amdhsa_user_sgpr_kernarg_preload_length 0
		.amdhsa_user_sgpr_kernarg_preload_offset 0
		.amdhsa_user_sgpr_private_segment_size 0
		.amdhsa_uses_dynamic_stack 0
		.amdhsa_enable_private_segment 0
		.amdhsa_system_sgpr_workgroup_id_x 1
		.amdhsa_system_sgpr_workgroup_id_y 0
		.amdhsa_system_sgpr_workgroup_id_z 0
		.amdhsa_system_sgpr_workgroup_info 0
		.amdhsa_system_vgpr_workitem_id 2
		.amdhsa_next_free_vgpr 256
		.amdhsa_next_free_sgpr 102
		.amdhsa_accum_offset 256
		.amdhsa_reserve_vcc 1
		.amdhsa_float_round_mode_32 0
		.amdhsa_float_round_mode_16_64 0
		.amdhsa_float_denorm_mode_32 3
		.amdhsa_float_denorm_mode_16_64 3
		.amdhsa_dx10_clamp 1
		.amdhsa_ieee_mode 1
		.amdhsa_fp16_overflow 0
		.amdhsa_tg_split 0
		.amdhsa_exception_fp_ieee_invalid_op 0
		.amdhsa_exception_fp_denorm_src 0
		.amdhsa_exception_fp_ieee_div_zero 0
		.amdhsa_exception_fp_ieee_overflow 0
		.amdhsa_exception_fp_ieee_underflow 0
		.amdhsa_exception_fp_ieee_inexact 0
		.amdhsa_exception_int_div_zero 0
	.end_amdhsa_kernel

amdhsa.kernels:
  - .agpr_count:     0
    .args:
      - .offset:         0
        .size:           136
        .value_kind:     by_value
      - .offset:         136
        .size:           4
        .value_kind:     hidden_block_count_x
      - .offset:         140
        .size:           4
        .value_kind:     hidden_block_count_y
      - .offset:         144
        .size:           4
        .value_kind:     hidden_block_count_z
      - .offset:         148
        .size:           2
        .value_kind:     hidden_group_size_x
      - .offset:         150
        .size:           2
        .value_kind:     hidden_group_size_y
      - .offset:         152
        .size:           2
        .value_kind:     hidden_group_size_z
      - .offset:         154
        .size:           2
        .value_kind:     hidden_remainder_x
      - .offset:         156
        .size:           2
        .value_kind:     hidden_remainder_y
      - .offset:         158
        .size:           2
        .value_kind:     hidden_remainder_z
      - .offset:         176
        .size:           8
        .value_kind:     hidden_global_offset_x
      - .offset:         184
        .size:           8
        .value_kind:     hidden_global_offset_y
      - .offset:         192
        .size:           8
        .value_kind:     hidden_global_offset_z
      - .offset:         200
        .size:           2
        .value_kind:     hidden_grid_dims
      - .offset:         224
        .size:           8
        .value_kind:     hidden_multigrid_sync_arg
      - .offset:         256
        .size:           4
        .value_kind:     hidden_dynamic_lds_size
    .group_segment_fixed_size: 0
    .kernarg_segment_align: 8
    .kernarg_segment_size: 392
    .language:       OpenCL C
    .language_version:
      - 2
      - 0
    .max_flat_workgroup_size: 512
    .name:           _Z10fwd_kernel6Params
    .private_segment_fixed_size: 0
    .sgpr_count:     108
    .sgpr_spill_count: 196
    .symbol:         _Z10fwd_kernel6Params.kd
    .uniform_work_group_size: 1
    .uses_dynamic_stack: false
    .vgpr_count:     256
    .vgpr_spill_count: 0
    .wavefront_size: 64
